# v110 + pre-K-loop vmcnt(0) drains deleted (store drain overlaps the next unit's first segments)
# baseline (speedup 1.0000x reference)
.LBB0_131:
	s_ashr_i32 s25, s24, 31
	s_lshl_b64 s[26:27], s[24:25], 21
	s_add_u32 s26, s46, s26
	s_addc_u32 s27, s47, s27
	s_and_b64 s[28:29], s[44:45], exec
	s_cselect_b32 s25, s27, s35
	s_cselect_b32 s61, s26, s34
	s_ashr_i32 s23, s22, 31
	s_lshl_b64 s[28:29], s[22:23], 21
	s_add_u32 s28, s48, s28
	s_addc_u32 s29, s49, s29
	s_and_b64 s[40:41], s[44:45], exec
	s_cselect_b32 s23, s29, s37
	s_cselect_b32 s62, s28, s36
	s_add_u32 s34, s34, 0x100080
	s_addc_u32 s35, s35, 0
	s_add_u32 s63, s36, 0x100
	v_mov_b32_e32 v42, 0
	s_addc_u32 s66, s37, 0
	s_mov_b32 s67, -2
	v_mov_b32_e32 v43, v42
	v_mov_b32_e32 v44, v42
	v_mov_b32_e32 v45, v42
	v_mov_b32_e32 v46, v42
	v_mov_b32_e32 v47, v42
	v_mov_b32_e32 v48, v42
	v_mov_b32_e32 v49, v42
	v_mov_b32_e32 v58, v42
	v_mov_b32_e32 v59, v42
	v_mov_b32_e32 v60, v42
	v_mov_b32_e32 v61, v42
	v_mov_b32_e32 v66, v42
	v_mov_b32_e32 v67, v42
	v_mov_b32_e32 v68, v42
	v_mov_b32_e32 v69, v42
	v_mov_b32_e32 v78, v42
	v_mov_b32_e32 v79, v42
	v_mov_b32_e32 v80, v42
	v_mov_b32_e32 v81, v42
	v_mov_b32_e32 v86, v42
	v_mov_b32_e32 v87, v42
	v_mov_b32_e32 v88, v42
	v_mov_b32_e32 v89, v42
	v_mov_b32_e32 v90, v42
	v_mov_b32_e32 v91, v42
	v_mov_b32_e32 v92, v42
	v_mov_b32_e32 v93, v42
	v_mov_b32_e32 v94, v42
	v_mov_b32_e32 v95, v42
	v_mov_b32_e32 v96, v42
	v_mov_b32_e32 v97, v42
	v_mov_b32_e32 v2, v42
	v_mov_b32_e32 v3, v42
	v_mov_b32_e32 v4, v42
	v_mov_b32_e32 v5, v42
	v_mov_b32_e32 v6, v42
	v_mov_b32_e32 v7, v42
	v_mov_b32_e32 v8, v42
	v_mov_b32_e32 v9, v42
	v_mov_b32_e32 v10, v42
	v_mov_b32_e32 v11, v42
	v_mov_b32_e32 v12, v42
	v_mov_b32_e32 v13, v42
	v_mov_b32_e32 v14, v42
	v_mov_b32_e32 v15, v42
	v_mov_b32_e32 v16, v42
	v_mov_b32_e32 v17, v42
	v_mov_b32_e32 v18, v42
	v_mov_b32_e32 v19, v42
	v_mov_b32_e32 v20, v42
	v_mov_b32_e32 v21, v42
	v_mov_b32_e32 v22, v42
	v_mov_b32_e32 v23, v42
	v_mov_b32_e32 v24, v42
	v_mov_b32_e32 v25, v42
	v_mov_b32_e32 v26, v42
	v_mov_b32_e32 v27, v42
	v_mov_b32_e32 v28, v42
	v_mov_b32_e32 v29, v42
	v_mov_b32_e32 v30, v42
	v_mov_b32_e32 v31, v42
	v_mov_b32_e32 v32, v42
	v_mov_b32_e32 v33, v42
	v_mov_b32_e32 v98, v42
	v_mov_b32_e32 v99, v42
	v_mov_b32_e32 v100, v42
	v_mov_b32_e32 v101, v42
	v_mov_b32_e32 v102, v42
	v_mov_b32_e32 v103, v42
	v_mov_b32_e32 v104, v42
	v_mov_b32_e32 v105, v42
	v_mov_b32_e32 v106, v42
	v_mov_b32_e32 v107, v42
	v_mov_b32_e32 v108, v42
	v_mov_b32_e32 v109, v42
	v_mov_b32_e32 v110, v42
	v_mov_b32_e32 v111, v42
	v_mov_b32_e32 v112, v42
	v_mov_b32_e32 v113, v42
	v_mov_b32_e32 v114, v42
	v_mov_b32_e32 v115, v42
	v_mov_b32_e32 v116, v42
	v_mov_b32_e32 v117, v42
	v_mov_b32_e32 v118, v42
	v_mov_b32_e32 v119, v42
	v_mov_b32_e32 v120, v42
	v_mov_b32_e32 v121, v42
	v_mov_b32_e32 v122, v42
	v_mov_b32_e32 v123, v42
	v_mov_b32_e32 v124, v42
	v_mov_b32_e32 v125, v42
	v_mov_b32_e32 v126, v42
	v_mov_b32_e32 v127, v42
	v_mov_b32_e32 v128, v42
	v_mov_b32_e32 v129, v42
	v_mov_b32_e32 v34, v42
	v_mov_b32_e32 v35, v42
	v_mov_b32_e32 v36, v42
	v_mov_b32_e32 v37, v42
	v_mov_b32_e32 v38, v42
	v_mov_b32_e32 v39, v42
	v_mov_b32_e32 v40, v42
	v_mov_b32_e32 v41, v42
	v_mov_b32_e32 v50, v42
	v_mov_b32_e32 v51, v42
	v_mov_b32_e32 v52, v42
	v_mov_b32_e32 v53, v42
	v_mov_b32_e32 v54, v42
	v_mov_b32_e32 v55, v42
	v_mov_b32_e32 v56, v42
	v_mov_b32_e32 v57, v42
	v_mov_b32_e32 v62, v42
	v_mov_b32_e32 v63, v42
	v_mov_b32_e32 v64, v42
	v_mov_b32_e32 v65, v42
	v_mov_b32_e32 v70, v42
	v_mov_b32_e32 v71, v42
	v_mov_b32_e32 v72, v42
	v_mov_b32_e32 v73, v42
	v_mov_b32_e32 v74, v42
	v_mov_b32_e32 v75, v42
	v_mov_b32_e32 v76, v42
	v_mov_b32_e32 v77, v42
	v_mov_b32_e32 v82, v42
	v_mov_b32_e32 v83, v42
	v_mov_b32_e32 v84, v42
	v_mov_b32_e32 v85, v42

.LBB0_1023:
	s_ashr_i32 s53, s52, 31
	s_lshl_b64 s[54:55], s[52:53], 21
	s_add_u32 s54, s60, s54
	s_addc_u32 s55, s61, s55
	s_and_b64 s[56:57], s[44:45], exec
	s_cselect_b32 s30, s55, s3
	s_cselect_b32 s53, s54, s2
	s_ashr_i32 s51, s50, 31
	s_lshl_b64 s[56:57], s[50:51], 21
	s_add_u32 s56, s62, s56
	s_addc_u32 s57, s63, s57
	s_and_b64 s[58:59], s[44:45], exec
	s_cselect_b32 s51, s57, s47
	s_cselect_b32 s79, s56, s46
	s_add_u32 s2, s2, 0x100080
	s_addc_u32 s3, s3, 0
	s_add_u32 s80, s46, 0x100
	v_mov_b32_e32 v2, 0
	s_addc_u32 s81, s47, 0
	s_mov_b32 s82, -2
	v_mov_b32_e32 v3, v2
	v_mov_b32_e32 v4, v2
	v_mov_b32_e32 v5, v2
	v_mov_b32_e32 v10, v2
	v_mov_b32_e32 v11, v2
	v_mov_b32_e32 v12, v2
	v_mov_b32_e32 v13, v2
	v_mov_b32_e32 v18, v2
	v_mov_b32_e32 v19, v2
	v_mov_b32_e32 v20, v2
	v_mov_b32_e32 v21, v2
	v_mov_b32_e32 v26, v2
	v_mov_b32_e32 v27, v2
	v_mov_b32_e32 v28, v2
	v_mov_b32_e32 v29, v2
	v_mov_b32_e32 v34, v2
	v_mov_b32_e32 v35, v2
	v_mov_b32_e32 v36, v2
	v_mov_b32_e32 v37, v2
	v_mov_b32_e32 v42, v2
	v_mov_b32_e32 v43, v2
	v_mov_b32_e32 v44, v2
	v_mov_b32_e32 v45, v2
	v_mov_b32_e32 v50, v2
	v_mov_b32_e32 v51, v2
	v_mov_b32_e32 v52, v2
	v_mov_b32_e32 v53, v2
	v_mov_b32_e32 v58, v2
	v_mov_b32_e32 v59, v2
	v_mov_b32_e32 v60, v2
	v_mov_b32_e32 v61, v2
	v_mov_b32_e32 v6, v2
	v_mov_b32_e32 v7, v2
	v_mov_b32_e32 v8, v2
	v_mov_b32_e32 v9, v2
	v_mov_b32_e32 v14, v2
	v_mov_b32_e32 v15, v2
	v_mov_b32_e32 v16, v2
	v_mov_b32_e32 v17, v2
	v_mov_b32_e32 v22, v2
	v_mov_b32_e32 v23, v2
	v_mov_b32_e32 v24, v2
	v_mov_b32_e32 v25, v2
	v_mov_b32_e32 v30, v2
	v_mov_b32_e32 v31, v2
	v_mov_b32_e32 v32, v2
	v_mov_b32_e32 v33, v2
	v_mov_b32_e32 v38, v2
	v_mov_b32_e32 v39, v2
	v_mov_b32_e32 v40, v2
	v_mov_b32_e32 v41, v2
	v_mov_b32_e32 v46, v2
	v_mov_b32_e32 v47, v2
	v_mov_b32_e32 v48, v2
	v_mov_b32_e32 v49, v2
	v_mov_b32_e32 v54, v2
	v_mov_b32_e32 v55, v2
	v_mov_b32_e32 v56, v2
	v_mov_b32_e32 v57, v2
	v_mov_b32_e32 v86, v2
	v_mov_b32_e32 v87, v2
	v_mov_b32_e32 v88, v2
	v_mov_b32_e32 v89, v2
	v_mov_b32_e32 v114, v2
	v_mov_b32_e32 v115, v2
	v_mov_b32_e32 v116, v2
	v_mov_b32_e32 v117, v2
	v_mov_b32_e32 v122, v2
	v_mov_b32_e32 v123, v2
	v_mov_b32_e32 v124, v2
	v_mov_b32_e32 v125, v2
	v_mov_b32_e32 v132, v2
	v_mov_b32_e32 v133, v2
	v_mov_b32_e32 v134, v2
	v_mov_b32_e32 v135, v2
	v_mov_b32_e32 v140, v2
	v_mov_b32_e32 v141, v2
	v_mov_b32_e32 v142, v2
	v_mov_b32_e32 v143, v2
	v_mov_b32_e32 v148, v2
	v_mov_b32_e32 v149, v2
	v_mov_b32_e32 v150, v2
	v_mov_b32_e32 v151, v2
	v_mov_b32_e32 v156, v2
	v_mov_b32_e32 v157, v2
	v_mov_b32_e32 v158, v2
	v_mov_b32_e32 v159, v2
	v_mov_b32_e32 v164, v2
	v_mov_b32_e32 v165, v2
	v_mov_b32_e32 v166, v2
	v_mov_b32_e32 v167, v2
	v_mov_b32_e32 v172, v2
	v_mov_b32_e32 v173, v2
	v_mov_b32_e32 v174, v2
	v_mov_b32_e32 v175, v2
	v_mov_b32_e32 v118, v2
	v_mov_b32_e32 v119, v2
	v_mov_b32_e32 v120, v2
	v_mov_b32_e32 v121, v2
	v_mov_b32_e32 v126, v2
	v_mov_b32_e32 v127, v2
	v_mov_b32_e32 v128, v2
	v_mov_b32_e32 v129, v2
	v_mov_b32_e32 v136, v2
	v_mov_b32_e32 v137, v2
	v_mov_b32_e32 v138, v2
	v_mov_b32_e32 v139, v2
	v_mov_b32_e32 v144, v2
	v_mov_b32_e32 v145, v2
	v_mov_b32_e32 v146, v2
	v_mov_b32_e32 v147, v2
	v_mov_b32_e32 v152, v2
	v_mov_b32_e32 v153, v2
	v_mov_b32_e32 v154, v2
	v_mov_b32_e32 v155, v2
	v_mov_b32_e32 v160, v2
	v_mov_b32_e32 v161, v2
	v_mov_b32_e32 v162, v2
	v_mov_b32_e32 v163, v2
	v_mov_b32_e32 v168, v2
	v_mov_b32_e32 v169, v2
	v_mov_b32_e32 v170, v2
	v_mov_b32_e32 v171, v2
	v_mov_b32_e32 v176, v2
	v_mov_b32_e32 v177, v2
	v_mov_b32_e32 v178, v2
	v_mov_b32_e32 v179, v2

.LBB0_1327:
	s_add_u32 s54, s24, 0x100
	v_mov_b32_e32 v2, 0
	s_addc_u32 s55, s25, 0
	s_mov_b32 s56, -2
	v_mov_b32_e32 v3, v2
	v_mov_b32_e32 v4, v2
	v_mov_b32_e32 v5, v2
	v_mov_b32_e32 v6, v2
	v_mov_b32_e32 v7, v2
	v_mov_b32_e32 v8, v2
	v_mov_b32_e32 v9, v2
	v_mov_b32_e32 v18, v2
	v_mov_b32_e32 v19, v2
	v_mov_b32_e32 v20, v2
	v_mov_b32_e32 v21, v2
	v_mov_b32_e32 v22, v2
	v_mov_b32_e32 v23, v2
	v_mov_b32_e32 v24, v2
	v_mov_b32_e32 v25, v2
	v_mov_b32_e32 v34, v2
	v_mov_b32_e32 v35, v2
	v_mov_b32_e32 v36, v2
	v_mov_b32_e32 v37, v2
	v_mov_b32_e32 v38, v2
	v_mov_b32_e32 v39, v2
	v_mov_b32_e32 v40, v2
	v_mov_b32_e32 v41, v2
	v_mov_b32_e32 v50, v2
	v_mov_b32_e32 v51, v2
	v_mov_b32_e32 v52, v2
	v_mov_b32_e32 v53, v2
	v_mov_b32_e32 v54, v2
	v_mov_b32_e32 v55, v2
	v_mov_b32_e32 v56, v2
	v_mov_b32_e32 v57, v2
	v_mov_b32_e32 v10, v2
	v_mov_b32_e32 v11, v2
	v_mov_b32_e32 v12, v2
	v_mov_b32_e32 v13, v2
	v_mov_b32_e32 v14, v2
	v_mov_b32_e32 v15, v2
	v_mov_b32_e32 v16, v2
	v_mov_b32_e32 v17, v2
	v_mov_b32_e32 v26, v2
	v_mov_b32_e32 v27, v2
	v_mov_b32_e32 v28, v2
	v_mov_b32_e32 v29, v2
	v_mov_b32_e32 v30, v2
	v_mov_b32_e32 v31, v2
	v_mov_b32_e32 v32, v2
	v_mov_b32_e32 v33, v2
	v_mov_b32_e32 v42, v2
	v_mov_b32_e32 v43, v2
	v_mov_b32_e32 v44, v2
	v_mov_b32_e32 v45, v2
	v_mov_b32_e32 v46, v2
	v_mov_b32_e32 v47, v2
	v_mov_b32_e32 v48, v2
	v_mov_b32_e32 v49, v2
	v_mov_b32_e32 v58, v2
	v_mov_b32_e32 v59, v2
	v_mov_b32_e32 v60, v2
	v_mov_b32_e32 v61, v2
	v_mov_b32_e32 v62, v2
	v_mov_b32_e32 v63, v2
	v_mov_b32_e32 v64, v2
	v_mov_b32_e32 v65, v2
	v_mov_b32_e32 v66, v2
	v_mov_b32_e32 v67, v2
	v_mov_b32_e32 v68, v2
	v_mov_b32_e32 v69, v2
	v_mov_b32_e32 v70, v2
	v_mov_b32_e32 v71, v2
	v_mov_b32_e32 v72, v2
	v_mov_b32_e32 v73, v2
	v_mov_b32_e32 v82, v2
	v_mov_b32_e32 v83, v2
	v_mov_b32_e32 v84, v2
	v_mov_b32_e32 v85, v2
	v_mov_b32_e32 v86, v2
	v_mov_b32_e32 v87, v2
	v_mov_b32_e32 v88, v2
	v_mov_b32_e32 v89, v2
	v_mov_b32_e32 v98, v2
	v_mov_b32_e32 v99, v2
	v_mov_b32_e32 v100, v2
	v_mov_b32_e32 v101, v2
	v_mov_b32_e32 v102, v2
	v_mov_b32_e32 v103, v2
	v_mov_b32_e32 v104, v2
	v_mov_b32_e32 v105, v2
	v_mov_b32_e32 v114, v2
	v_mov_b32_e32 v115, v2
	v_mov_b32_e32 v116, v2
	v_mov_b32_e32 v117, v2
	v_mov_b32_e32 v118, v2
	v_mov_b32_e32 v119, v2
	v_mov_b32_e32 v120, v2
	v_mov_b32_e32 v121, v2
	v_mov_b32_e32 v74, v2
	v_mov_b32_e32 v75, v2
	v_mov_b32_e32 v76, v2
	v_mov_b32_e32 v77, v2
	v_mov_b32_e32 v78, v2
	v_mov_b32_e32 v79, v2
	v_mov_b32_e32 v80, v2
	v_mov_b32_e32 v81, v2
	v_mov_b32_e32 v90, v2
	v_mov_b32_e32 v91, v2
	v_mov_b32_e32 v92, v2
	v_mov_b32_e32 v93, v2
	v_mov_b32_e32 v94, v2
	v_mov_b32_e32 v95, v2
	v_mov_b32_e32 v96, v2
	v_mov_b32_e32 v97, v2
	v_mov_b32_e32 v106, v2
	v_mov_b32_e32 v107, v2
	v_mov_b32_e32 v108, v2
	v_mov_b32_e32 v109, v2
	v_mov_b32_e32 v110, v2
	v_mov_b32_e32 v111, v2
	v_mov_b32_e32 v112, v2
	v_mov_b32_e32 v113, v2
	v_mov_b32_e32 v122, v2
	v_mov_b32_e32 v123, v2
	v_mov_b32_e32 v124, v2
	v_mov_b32_e32 v125, v2
	v_mov_b32_e32 v126, v2
	v_mov_b32_e32 v127, v2
	v_mov_b32_e32 v128, v2
	v_mov_b32_e32 v129, v2

.LBB0_1353:
	s_add_u32 s57, s24, 0x100
	v_mov_b32_e32 v2, 0
	s_addc_u32 s58, s25, 0
	s_mov_b32 s59, -2
	v_mov_b32_e32 v3, v2
	v_mov_b32_e32 v4, v2
	v_mov_b32_e32 v5, v2
	v_mov_b32_e32 v6, v2
	v_mov_b32_e32 v7, v2
	v_mov_b32_e32 v8, v2
	v_mov_b32_e32 v9, v2
	v_mov_b32_e32 v18, v2
	v_mov_b32_e32 v19, v2
	v_mov_b32_e32 v20, v2
	v_mov_b32_e32 v21, v2
	v_mov_b32_e32 v22, v2
	v_mov_b32_e32 v23, v2
	v_mov_b32_e32 v24, v2
	v_mov_b32_e32 v25, v2
	v_mov_b32_e32 v34, v2
	v_mov_b32_e32 v35, v2
	v_mov_b32_e32 v36, v2
	v_mov_b32_e32 v37, v2
	v_mov_b32_e32 v38, v2
	v_mov_b32_e32 v39, v2
	v_mov_b32_e32 v40, v2
	v_mov_b32_e32 v41, v2
	v_mov_b32_e32 v50, v2
	v_mov_b32_e32 v51, v2
	v_mov_b32_e32 v52, v2
	v_mov_b32_e32 v53, v2
	v_mov_b32_e32 v54, v2
	v_mov_b32_e32 v55, v2
	v_mov_b32_e32 v56, v2
	v_mov_b32_e32 v57, v2
	v_mov_b32_e32 v10, v2
	v_mov_b32_e32 v11, v2
	v_mov_b32_e32 v12, v2
	v_mov_b32_e32 v13, v2
	v_mov_b32_e32 v14, v2
	v_mov_b32_e32 v15, v2
	v_mov_b32_e32 v16, v2
	v_mov_b32_e32 v17, v2
	v_mov_b32_e32 v26, v2
	v_mov_b32_e32 v27, v2
	v_mov_b32_e32 v28, v2
	v_mov_b32_e32 v29, v2
	v_mov_b32_e32 v30, v2
	v_mov_b32_e32 v31, v2
	v_mov_b32_e32 v32, v2
	v_mov_b32_e32 v33, v2
	v_mov_b32_e32 v42, v2
	v_mov_b32_e32 v43, v2
	v_mov_b32_e32 v44, v2
	v_mov_b32_e32 v45, v2
	v_mov_b32_e32 v46, v2
	v_mov_b32_e32 v47, v2
	v_mov_b32_e32 v48, v2
	v_mov_b32_e32 v49, v2
	v_mov_b32_e32 v58, v2
	v_mov_b32_e32 v59, v2
	v_mov_b32_e32 v60, v2
	v_mov_b32_e32 v61, v2
	v_mov_b32_e32 v62, v2
	v_mov_b32_e32 v63, v2
	v_mov_b32_e32 v64, v2
	v_mov_b32_e32 v65, v2
	v_mov_b32_e32 v66, v2
	v_mov_b32_e32 v67, v2
	v_mov_b32_e32 v68, v2
	v_mov_b32_e32 v69, v2
	v_mov_b32_e32 v70, v2
	v_mov_b32_e32 v71, v2
	v_mov_b32_e32 v72, v2
	v_mov_b32_e32 v73, v2
	v_mov_b32_e32 v82, v2
	v_mov_b32_e32 v83, v2
	v_mov_b32_e32 v84, v2
	v_mov_b32_e32 v85, v2
	v_mov_b32_e32 v86, v2
	v_mov_b32_e32 v87, v2
	v_mov_b32_e32 v88, v2
	v_mov_b32_e32 v89, v2
	v_mov_b32_e32 v98, v2
	v_mov_b32_e32 v99, v2
	v_mov_b32_e32 v100, v2
	v_mov_b32_e32 v101, v2
	v_mov_b32_e32 v102, v2
	v_mov_b32_e32 v103, v2
	v_mov_b32_e32 v104, v2
	v_mov_b32_e32 v105, v2
	v_mov_b32_e32 v114, v2
	v_mov_b32_e32 v115, v2
	v_mov_b32_e32 v116, v2
	v_mov_b32_e32 v117, v2
	v_mov_b32_e32 v118, v2
	v_mov_b32_e32 v119, v2
	v_mov_b32_e32 v120, v2
	v_mov_b32_e32 v121, v2
	v_mov_b32_e32 v74, v2
	v_mov_b32_e32 v75, v2
	v_mov_b32_e32 v76, v2
	v_mov_b32_e32 v77, v2
	v_mov_b32_e32 v78, v2
	v_mov_b32_e32 v79, v2
	v_mov_b32_e32 v80, v2
	v_mov_b32_e32 v81, v2
	v_mov_b32_e32 v90, v2
	v_mov_b32_e32 v91, v2
	v_mov_b32_e32 v92, v2
	v_mov_b32_e32 v93, v2
	v_mov_b32_e32 v94, v2
	v_mov_b32_e32 v95, v2
	v_mov_b32_e32 v96, v2
	v_mov_b32_e32 v97, v2
	v_mov_b32_e32 v106, v2
	v_mov_b32_e32 v107, v2
	v_mov_b32_e32 v108, v2
	v_mov_b32_e32 v109, v2
	v_mov_b32_e32 v110, v2
	v_mov_b32_e32 v111, v2
	v_mov_b32_e32 v112, v2
	v_mov_b32_e32 v113, v2
	v_mov_b32_e32 v122, v2
	v_mov_b32_e32 v123, v2
	v_mov_b32_e32 v124, v2
	v_mov_b32_e32 v125, v2
	v_mov_b32_e32 v126, v2
	v_mov_b32_e32 v127, v2
	v_mov_b32_e32 v128, v2
	v_mov_b32_e32 v129, v2

.LBB0_1404:
	s_add_u32 s51, s22, 0x100
	v_mov_b32_e32 v2, 0
	s_addc_u32 s52, s23, 0
	s_mov_b32 s53, -2
	v_mov_b32_e32 v3, v2
	v_mov_b32_e32 v4, v2
	s_waitcnt lgkmcnt(0)
	v_mov_b32_e32 v5, v2
	v_mov_b32_e32 v6, v2
	v_mov_b32_e32 v7, v2
	v_mov_b32_e32 v8, v2
	v_mov_b32_e32 v9, v2
	v_mov_b32_e32 v18, v2
	v_mov_b32_e32 v19, v2
	v_mov_b32_e32 v20, v2
	v_mov_b32_e32 v21, v2
	v_mov_b32_e32 v22, v2
	v_mov_b32_e32 v23, v2
	v_mov_b32_e32 v24, v2
	v_mov_b32_e32 v25, v2
	v_mov_b32_e32 v34, v2
	v_mov_b32_e32 v35, v2
	v_mov_b32_e32 v36, v2
	v_mov_b32_e32 v37, v2
	v_mov_b32_e32 v38, v2
	v_mov_b32_e32 v39, v2
	v_mov_b32_e32 v40, v2
	v_mov_b32_e32 v41, v2
	v_mov_b32_e32 v50, v2
	v_mov_b32_e32 v51, v2
	v_mov_b32_e32 v52, v2
	v_mov_b32_e32 v53, v2
	v_mov_b32_e32 v54, v2
	v_mov_b32_e32 v55, v2
	v_mov_b32_e32 v56, v2
	v_mov_b32_e32 v57, v2
	v_mov_b32_e32 v10, v2
	v_mov_b32_e32 v11, v2
	v_mov_b32_e32 v12, v2
	v_mov_b32_e32 v13, v2
	v_mov_b32_e32 v14, v2
	v_mov_b32_e32 v15, v2
	v_mov_b32_e32 v16, v2
	v_mov_b32_e32 v17, v2
	v_mov_b32_e32 v26, v2
	v_mov_b32_e32 v27, v2
	v_mov_b32_e32 v28, v2
	v_mov_b32_e32 v29, v2
	v_mov_b32_e32 v30, v2
	v_mov_b32_e32 v31, v2
	v_mov_b32_e32 v32, v2
	v_mov_b32_e32 v33, v2
	v_mov_b32_e32 v42, v2
	v_mov_b32_e32 v43, v2
	v_mov_b32_e32 v44, v2
	v_mov_b32_e32 v45, v2
	v_mov_b32_e32 v46, v2
	v_mov_b32_e32 v47, v2
	v_mov_b32_e32 v48, v2
	v_mov_b32_e32 v49, v2
	v_mov_b32_e32 v58, v2
	v_mov_b32_e32 v59, v2
	v_mov_b32_e32 v60, v2
	v_mov_b32_e32 v61, v2
	v_mov_b32_e32 v62, v2
	v_mov_b32_e32 v63, v2
	v_mov_b32_e32 v64, v2
	v_mov_b32_e32 v65, v2
	v_mov_b32_e32 v66, v2
	v_mov_b32_e32 v67, v2
	v_mov_b32_e32 v68, v2
	v_mov_b32_e32 v69, v2
	v_mov_b32_e32 v70, v2
	v_mov_b32_e32 v71, v2
	v_mov_b32_e32 v72, v2
	v_mov_b32_e32 v73, v2
	v_mov_b32_e32 v82, v2
	v_mov_b32_e32 v83, v2
	v_mov_b32_e32 v84, v2
	v_mov_b32_e32 v85, v2
	v_mov_b32_e32 v86, v2
	v_mov_b32_e32 v87, v2
	v_mov_b32_e32 v88, v2
	v_mov_b32_e32 v89, v2
	v_mov_b32_e32 v98, v2
	v_mov_b32_e32 v99, v2
	v_mov_b32_e32 v100, v2
	v_mov_b32_e32 v101, v2
	v_mov_b32_e32 v102, v2
	v_mov_b32_e32 v103, v2
	v_mov_b32_e32 v104, v2
	v_mov_b32_e32 v105, v2
	v_mov_b32_e32 v114, v2
	v_mov_b32_e32 v115, v2
	v_mov_b32_e32 v116, v2
	v_mov_b32_e32 v117, v2
	v_mov_b32_e32 v118, v2
	v_mov_b32_e32 v119, v2
	v_mov_b32_e32 v120, v2
	v_mov_b32_e32 v121, v2
	v_mov_b32_e32 v74, v2
	v_mov_b32_e32 v75, v2
	v_mov_b32_e32 v76, v2
	v_mov_b32_e32 v77, v2
	v_mov_b32_e32 v78, v2
	v_mov_b32_e32 v79, v2
	v_mov_b32_e32 v80, v2
	v_mov_b32_e32 v81, v2
	v_mov_b32_e32 v90, v2
	v_mov_b32_e32 v91, v2
	v_mov_b32_e32 v92, v2
	v_mov_b32_e32 v93, v2
	v_mov_b32_e32 v94, v2
	v_mov_b32_e32 v95, v2
	v_mov_b32_e32 v96, v2
	v_mov_b32_e32 v97, v2
	v_mov_b32_e32 v106, v2
	v_mov_b32_e32 v107, v2
	v_mov_b32_e32 v108, v2
	v_mov_b32_e32 v109, v2
	v_mov_b32_e32 v110, v2
	v_mov_b32_e32 v111, v2
	v_mov_b32_e32 v112, v2
	v_mov_b32_e32 v113, v2
	v_mov_b32_e32 v122, v2
	v_mov_b32_e32 v123, v2
	v_mov_b32_e32 v124, v2
	v_mov_b32_e32 v125, v2
	v_mov_b32_e32 v126, v2
	v_mov_b32_e32 v127, v2
	v_mov_b32_e32 v128, v2
	v_mov_b32_e32 v129, v2
